# v67 + spatial-gating sample item: the 8-step dependent load ladder replaced by one batch of loads (lane-indexed sums of squares, 8 weights, 8 rows), later tokens masked by zero weight
# baseline (speedup 1.0000x reference)
.LBB0_609:
	s_and_b64 vcc, exec, s[4:5]
	s_cbranch_vccnz .LBB0_608
	v_mov_b32_e32 v2, v0
	s_bfe_u32 s14, s13, 0x30003
	v_bfe_u32 v33, v2, 4, 2
	v_lshlrev_b32_e32 v18, 16, v33
	v_and_b32_e32 v34, 63, v2
	v_lshl_add_u64 v[2:3], s[50:51], 0, v[18:19]
	s_lshl_b32 s0, s14, 9
	v_lshl_add_u64 v[30:31], v[2:3], 0, s[0:1]
	s_ashr_i32 s0, s13, 3
	s_and_b32 s0, s0, -8
	s_add_i32 s6, s0, 0x4000
	s_ashr_i32 s7, s6, 31
	s_lshl_b64 s[16:17], s[6:7], 3
	s_add_u32 s16, s62, s16
	v_lshlrev_b32_e32 v6, 5, v34
	s_addc_u32 s17, s63, s17
	global_load_dwordx4 v[2:5], v6, s[48:49] offset:16
	s_nop 0
	global_load_dwordx4 v[6:9], v6, s[48:49]
	v_lshlrev_b32_e32 v18, 4, v34
	v_lshl_add_u64 v[28:29], s[36:37], 0, v[18:19]
	v_and_b32_e32 v18, 7, v34
	v_lshlrev_b32_e32 v18, 3, v18
	global_load_dwordx2 v[10:11], v18, s[16:17] sc1
	global_load_dword v40, v[30:31], off
	global_load_dword v41, v[30:31], off offset:4
	global_load_dword v42, v[30:31], off offset:8
	global_load_dword v43, v[30:31], off offset:12
	global_load_dword v44, v[30:31], off offset:16
	global_load_dword v45, v[30:31], off offset:20
	global_load_dword v46, v[30:31], off offset:24
	global_load_dword v47, v[30:31], off offset:28
	s_lshl_b64 s[18:19], s[6:7], 10
	v_lshl_add_u64 v[36:37], v[28:29], 0, s[18:19]
	global_load_dwordx4 v[48:51], v[36:37], off
	global_load_dwordx4 v[52:55], v[36:37], off offset:1024
	global_load_dwordx4 v[56:59], v[36:37], off offset:2048
	global_load_dwordx4 v[60:63], v[36:37], off offset:3072
	s_add_u32 s18, s18, 0x1000
	s_addc_u32 s19, s19, 0
	v_lshl_add_u64 v[38:39], v[28:29], 0, s[18:19]
	global_load_dwordx4 v[64:67], v[38:39], off
	global_load_dwordx4 v[68:71], v[38:39], off offset:1024
	global_load_dwordx4 v[72:75], v[38:39], off offset:2048
	global_load_dwordx4 v[76:79], v[38:39], off offset:3072
	v_mov_b32_e32 v20, 0
	v_mov_b32_e32 v21, 0
	v_mov_b32_e32 v22, 0
	v_mov_b32_e32 v23, 0
	v_mov_b32_e32 v24, 0
	v_mov_b32_e32 v25, 0
	v_mov_b32_e32 v26, 0
	v_mov_b32_e32 v27, 0
	v_mov_b32_e32 v12, 0
	v_mov_b32_e32 v13, 0
	v_mov_b32_e32 v14, 0
	v_mov_b32_e32 v15, 0
	v_mov_b32_e32 v16, 0
	v_mov_b32_e32 v17, 0
	s_waitcnt vmcnt(16)
	v_ffbh_u32_e32 v80, v11
	v_min_u32_e32 v80, 32, v80
	v_lshlrev_b64 v[10:11], v80, v[10:11]
	v_min_u32_e32 v10, 1, v10
	v_or_b32_e32 v10, v11, v10
	v_cvt_f32_u32_e32 v10, v10
	v_sub_u32_e32 v11, 32, v80
	v_ldexp_f32 v10, v10, v11
	v_fmamk_f32 v10, v10, 0x31000000, v32
	v_rsq_f32_e32 v80, v10
	s_nop 1
	v_mov_b32_e32 v10, 0
	v_mov_b32_e32 v11, 0
	s_waitcnt vmcnt(8)
	v_readlane_b32 s18, v80, 0
	s_cmp_ge_u32 s14, 0
	s_cselect_b64 vcc, -1, 0
	s_waitcnt vmcnt(7)
	v_lshlrev_b32_e32 v82, 16, v48
	v_and_b32_e32 v83, 0xffff0000, v48
	v_lshlrev_b32_e32 v84, 16, v49
	v_and_b32_e32 v85, 0xffff0000, v49
	v_lshlrev_b32_e32 v86, 16, v50
	v_and_b32_e32 v87, 0xffff0000, v50
	v_lshlrev_b32_e32 v88, 16, v51
	v_and_b32_e32 v89, 0xffff0000, v51
	v_cndmask_b32_e32 v81, 0, v40, vcc
	v_pk_mul_f32 v[82:83], v[6:7], v[82:83]
	v_pk_mul_f32 v[84:85], v[8:9], v[84:85]
	v_pk_mul_f32 v[86:87], v[2:3], v[86:87]
	v_pk_mul_f32 v[88:89], v[4:5], v[88:89]
	s_cmp_eq_u32 s14, 0
	s_cselect_b64 vcc, -1, 0
	v_mul_f32_e32 v82, s18, v82
	v_mul_f32_e32 v83, s18, v83
	v_mul_f32_e32 v84, s18, v84
	v_mul_f32_e32 v85, s18, v85
	v_mul_f32_e32 v86, s18, v86
	v_mul_f32_e32 v87, s18, v87
	v_mul_f32_e32 v88, s18, v88
	v_mul_f32_e32 v89, s18, v89
	v_fmac_f32_e32 v22, v81, v82
	v_fmac_f32_e32 v23, v81, v83
	v_fmac_f32_e32 v26, v81, v84
	v_fmac_f32_e32 v27, v81, v85
	v_fmac_f32_e32 v20, v81, v86
	v_fmac_f32_e32 v21, v81, v87
	v_fmac_f32_e32 v24, v81, v88
	v_fmac_f32_e32 v25, v81, v89
	v_cndmask_b32_e32 v10, v10, v82, vcc
	v_cndmask_b32_e32 v11, v11, v83, vcc
	v_cndmask_b32_e32 v12, v12, v84, vcc
	v_cndmask_b32_e32 v13, v13, v85, vcc
	v_cndmask_b32_e32 v14, v14, v86, vcc
	v_cndmask_b32_e32 v15, v15, v87, vcc
	v_cndmask_b32_e32 v16, v16, v88, vcc
	v_cndmask_b32_e32 v17, v17, v89, vcc
	v_readlane_b32 s18, v80, 1
	s_cmp_ge_u32 s14, 1
	s_cselect_b64 vcc, -1, 0
	s_waitcnt vmcnt(6)
	v_lshlrev_b32_e32 v82, 16, v52
	v_and_b32_e32 v83, 0xffff0000, v52
	v_lshlrev_b32_e32 v84, 16, v53
	v_and_b32_e32 v85, 0xffff0000, v53
	v_lshlrev_b32_e32 v86, 16, v54
	v_and_b32_e32 v87, 0xffff0000, v54
	v_lshlrev_b32_e32 v88, 16, v55
	v_and_b32_e32 v89, 0xffff0000, v55
	v_cndmask_b32_e32 v81, 0, v41, vcc
	v_pk_mul_f32 v[82:83], v[6:7], v[82:83]
	v_pk_mul_f32 v[84:85], v[8:9], v[84:85]
	v_pk_mul_f32 v[86:87], v[2:3], v[86:87]
	v_pk_mul_f32 v[88:89], v[4:5], v[88:89]
	s_cmp_eq_u32 s14, 1
	s_cselect_b64 vcc, -1, 0
	v_mul_f32_e32 v82, s18, v82
	v_mul_f32_e32 v83, s18, v83
	v_mul_f32_e32 v84, s18, v84
	v_mul_f32_e32 v85, s18, v85
	v_mul_f32_e32 v86, s18, v86
	v_mul_f32_e32 v87, s18, v87
	v_mul_f32_e32 v88, s18, v88
	v_mul_f32_e32 v89, s18, v89
	v_fmac_f32_e32 v22, v81, v82
	v_fmac_f32_e32 v23, v81, v83
	v_fmac_f32_e32 v26, v81, v84
	v_fmac_f32_e32 v27, v81, v85
	v_fmac_f32_e32 v20, v81, v86
	v_fmac_f32_e32 v21, v81, v87
	v_fmac_f32_e32 v24, v81, v88
	v_fmac_f32_e32 v25, v81, v89
	v_cndmask_b32_e32 v10, v10, v82, vcc
	v_cndmask_b32_e32 v11, v11, v83, vcc
	v_cndmask_b32_e32 v12, v12, v84, vcc
	v_cndmask_b32_e32 v13, v13, v85, vcc
	v_cndmask_b32_e32 v14, v14, v86, vcc
	v_cndmask_b32_e32 v15, v15, v87, vcc
	v_cndmask_b32_e32 v16, v16, v88, vcc
	v_cndmask_b32_e32 v17, v17, v89, vcc
	v_readlane_b32 s18, v80, 2
	s_cmp_ge_u32 s14, 2
	s_cselect_b64 vcc, -1, 0
	s_waitcnt vmcnt(5)
	v_lshlrev_b32_e32 v82, 16, v56
	v_and_b32_e32 v83, 0xffff0000, v56
	v_lshlrev_b32_e32 v84, 16, v57
	v_and_b32_e32 v85, 0xffff0000, v57
	v_lshlrev_b32_e32 v86, 16, v58
	v_and_b32_e32 v87, 0xffff0000, v58
	v_lshlrev_b32_e32 v88, 16, v59
	v_and_b32_e32 v89, 0xffff0000, v59
	v_cndmask_b32_e32 v81, 0, v42, vcc
	v_pk_mul_f32 v[82:83], v[6:7], v[82:83]
	v_pk_mul_f32 v[84:85], v[8:9], v[84:85]
	v_pk_mul_f32 v[86:87], v[2:3], v[86:87]
	v_pk_mul_f32 v[88:89], v[4:5], v[88:89]
	s_cmp_eq_u32 s14, 2
	s_cselect_b64 vcc, -1, 0
	v_mul_f32_e32 v82, s18, v82
	v_mul_f32_e32 v83, s18, v83
	v_mul_f32_e32 v84, s18, v84
	v_mul_f32_e32 v85, s18, v85
	v_mul_f32_e32 v86, s18, v86
	v_mul_f32_e32 v87, s18, v87
	v_mul_f32_e32 v88, s18, v88
	v_mul_f32_e32 v89, s18, v89
	v_fmac_f32_e32 v22, v81, v82
	v_fmac_f32_e32 v23, v81, v83
	v_fmac_f32_e32 v26, v81, v84
	v_fmac_f32_e32 v27, v81, v85
	v_fmac_f32_e32 v20, v81, v86
	v_fmac_f32_e32 v21, v81, v87
	v_fmac_f32_e32 v24, v81, v88
	v_fmac_f32_e32 v25, v81, v89
	v_cndmask_b32_e32 v10, v10, v82, vcc
	v_cndmask_b32_e32 v11, v11, v83, vcc
	v_cndmask_b32_e32 v12, v12, v84, vcc
	v_cndmask_b32_e32 v13, v13, v85, vcc
	v_cndmask_b32_e32 v14, v14, v86, vcc
	v_cndmask_b32_e32 v15, v15, v87, vcc
	v_cndmask_b32_e32 v16, v16, v88, vcc
	v_cndmask_b32_e32 v17, v17, v89, vcc
	v_readlane_b32 s18, v80, 3
	s_cmp_ge_u32 s14, 3
	s_cselect_b64 vcc, -1, 0
	s_waitcnt vmcnt(4)
	v_lshlrev_b32_e32 v82, 16, v60
	v_and_b32_e32 v83, 0xffff0000, v60
	v_lshlrev_b32_e32 v84, 16, v61
	v_and_b32_e32 v85, 0xffff0000, v61
	v_lshlrev_b32_e32 v86, 16, v62
	v_and_b32_e32 v87, 0xffff0000, v62
	v_lshlrev_b32_e32 v88, 16, v63
	v_and_b32_e32 v89, 0xffff0000, v63
	v_cndmask_b32_e32 v81, 0, v43, vcc
	v_pk_mul_f32 v[82:83], v[6:7], v[82:83]
	v_pk_mul_f32 v[84:85], v[8:9], v[84:85]
	v_pk_mul_f32 v[86:87], v[2:3], v[86:87]
	v_pk_mul_f32 v[88:89], v[4:5], v[88:89]
	s_cmp_eq_u32 s14, 3
	s_cselect_b64 vcc, -1, 0
	v_mul_f32_e32 v82, s18, v82
	v_mul_f32_e32 v83, s18, v83
	v_mul_f32_e32 v84, s18, v84
	v_mul_f32_e32 v85, s18, v85
	v_mul_f32_e32 v86, s18, v86
	v_mul_f32_e32 v87, s18, v87
	v_mul_f32_e32 v88, s18, v88
	v_mul_f32_e32 v89, s18, v89
	v_fmac_f32_e32 v22, v81, v82
	v_fmac_f32_e32 v23, v81, v83
	v_fmac_f32_e32 v26, v81, v84
	v_fmac_f32_e32 v27, v81, v85
	v_fmac_f32_e32 v20, v81, v86
	v_fmac_f32_e32 v21, v81, v87
	v_fmac_f32_e32 v24, v81, v88
	v_fmac_f32_e32 v25, v81, v89
	v_cndmask_b32_e32 v10, v10, v82, vcc
	v_cndmask_b32_e32 v11, v11, v83, vcc
	v_cndmask_b32_e32 v12, v12, v84, vcc
	v_cndmask_b32_e32 v13, v13, v85, vcc
	v_cndmask_b32_e32 v14, v14, v86, vcc
	v_cndmask_b32_e32 v15, v15, v87, vcc
	v_cndmask_b32_e32 v16, v16, v88, vcc
	v_cndmask_b32_e32 v17, v17, v89, vcc
	v_readlane_b32 s18, v80, 4
	s_cmp_ge_u32 s14, 4
	s_cselect_b64 vcc, -1, 0
	s_waitcnt vmcnt(3)
	v_lshlrev_b32_e32 v82, 16, v64
	v_and_b32_e32 v83, 0xffff0000, v64
	v_lshlrev_b32_e32 v84, 16, v65
	v_and_b32_e32 v85, 0xffff0000, v65
	v_lshlrev_b32_e32 v86, 16, v66
	v_and_b32_e32 v87, 0xffff0000, v66
	v_lshlrev_b32_e32 v88, 16, v67
	v_and_b32_e32 v89, 0xffff0000, v67
	v_cndmask_b32_e32 v81, 0, v44, vcc
	v_pk_mul_f32 v[82:83], v[6:7], v[82:83]
	v_pk_mul_f32 v[84:85], v[8:9], v[84:85]
	v_pk_mul_f32 v[86:87], v[2:3], v[86:87]
	v_pk_mul_f32 v[88:89], v[4:5], v[88:89]
	s_cmp_eq_u32 s14, 4
	s_cselect_b64 vcc, -1, 0
	v_mul_f32_e32 v82, s18, v82
	v_mul_f32_e32 v83, s18, v83
	v_mul_f32_e32 v84, s18, v84
	v_mul_f32_e32 v85, s18, v85
	v_mul_f32_e32 v86, s18, v86
	v_mul_f32_e32 v87, s18, v87
	v_mul_f32_e32 v88, s18, v88
	v_mul_f32_e32 v89, s18, v89
	v_fmac_f32_e32 v22, v81, v82
	v_fmac_f32_e32 v23, v81, v83
	v_fmac_f32_e32 v26, v81, v84
	v_fmac_f32_e32 v27, v81, v85
	v_fmac_f32_e32 v20, v81, v86
	v_fmac_f32_e32 v21, v81, v87
	v_fmac_f32_e32 v24, v81, v88
	v_fmac_f32_e32 v25, v81, v89
	v_cndmask_b32_e32 v10, v10, v82, vcc
	v_cndmask_b32_e32 v11, v11, v83, vcc
	v_cndmask_b32_e32 v12, v12, v84, vcc
	v_cndmask_b32_e32 v13, v13, v85, vcc
	v_cndmask_b32_e32 v14, v14, v86, vcc
	v_cndmask_b32_e32 v15, v15, v87, vcc
	v_cndmask_b32_e32 v16, v16, v88, vcc
	v_cndmask_b32_e32 v17, v17, v89, vcc
	v_readlane_b32 s18, v80, 5
	s_cmp_ge_u32 s14, 5
	s_cselect_b64 vcc, -1, 0
	s_waitcnt vmcnt(2)
	v_lshlrev_b32_e32 v82, 16, v68
	v_and_b32_e32 v83, 0xffff0000, v68
	v_lshlrev_b32_e32 v84, 16, v69
	v_and_b32_e32 v85, 0xffff0000, v69
	v_lshlrev_b32_e32 v86, 16, v70
	v_and_b32_e32 v87, 0xffff0000, v70
	v_lshlrev_b32_e32 v88, 16, v71
	v_and_b32_e32 v89, 0xffff0000, v71
	v_cndmask_b32_e32 v81, 0, v45, vcc
	v_pk_mul_f32 v[82:83], v[6:7], v[82:83]
	v_pk_mul_f32 v[84:85], v[8:9], v[84:85]
	v_pk_mul_f32 v[86:87], v[2:3], v[86:87]
	v_pk_mul_f32 v[88:89], v[4:5], v[88:89]
	s_cmp_eq_u32 s14, 5
	s_cselect_b64 vcc, -1, 0
	v_mul_f32_e32 v82, s18, v82
	v_mul_f32_e32 v83, s18, v83
	v_mul_f32_e32 v84, s18, v84
	v_mul_f32_e32 v85, s18, v85
	v_mul_f32_e32 v86, s18, v86
	v_mul_f32_e32 v87, s18, v87
	v_mul_f32_e32 v88, s18, v88
	v_mul_f32_e32 v89, s18, v89
	v_fmac_f32_e32 v22, v81, v82
	v_fmac_f32_e32 v23, v81, v83
	v_fmac_f32_e32 v26, v81, v84
	v_fmac_f32_e32 v27, v81, v85
	v_fmac_f32_e32 v20, v81, v86
	v_fmac_f32_e32 v21, v81, v87
	v_fmac_f32_e32 v24, v81, v88
	v_fmac_f32_e32 v25, v81, v89
	v_cndmask_b32_e32 v10, v10, v82, vcc
	v_cndmask_b32_e32 v11, v11, v83, vcc
	v_cndmask_b32_e32 v12, v12, v84, vcc
	v_cndmask_b32_e32 v13, v13, v85, vcc
	v_cndmask_b32_e32 v14, v14, v86, vcc
	v_cndmask_b32_e32 v15, v15, v87, vcc
	v_cndmask_b32_e32 v16, v16, v88, vcc
	v_cndmask_b32_e32 v17, v17, v89, vcc
	v_readlane_b32 s18, v80, 6
	s_cmp_ge_u32 s14, 6
	s_cselect_b64 vcc, -1, 0
	s_waitcnt vmcnt(1)
	v_lshlrev_b32_e32 v82, 16, v72
	v_and_b32_e32 v83, 0xffff0000, v72
	v_lshlrev_b32_e32 v84, 16, v73
	v_and_b32_e32 v85, 0xffff0000, v73
	v_lshlrev_b32_e32 v86, 16, v74
	v_and_b32_e32 v87, 0xffff0000, v74
	v_lshlrev_b32_e32 v88, 16, v75
	v_and_b32_e32 v89, 0xffff0000, v75
	v_cndmask_b32_e32 v81, 0, v46, vcc
	v_pk_mul_f32 v[82:83], v[6:7], v[82:83]
	v_pk_mul_f32 v[84:85], v[8:9], v[84:85]
	v_pk_mul_f32 v[86:87], v[2:3], v[86:87]
	v_pk_mul_f32 v[88:89], v[4:5], v[88:89]
	s_cmp_eq_u32 s14, 6
	s_cselect_b64 vcc, -1, 0
	v_mul_f32_e32 v82, s18, v82
	v_mul_f32_e32 v83, s18, v83
	v_mul_f32_e32 v84, s18, v84
	v_mul_f32_e32 v85, s18, v85
	v_mul_f32_e32 v86, s18, v86
	v_mul_f32_e32 v87, s18, v87
	v_mul_f32_e32 v88, s18, v88
	v_mul_f32_e32 v89, s18, v89
	v_fmac_f32_e32 v22, v81, v82
	v_fmac_f32_e32 v23, v81, v83
	v_fmac_f32_e32 v26, v81, v84
	v_fmac_f32_e32 v27, v81, v85
	v_fmac_f32_e32 v20, v81, v86
	v_fmac_f32_e32 v21, v81, v87
	v_fmac_f32_e32 v24, v81, v88
	v_fmac_f32_e32 v25, v81, v89
	v_cndmask_b32_e32 v10, v10, v82, vcc
	v_cndmask_b32_e32 v11, v11, v83, vcc
	v_cndmask_b32_e32 v12, v12, v84, vcc
	v_cndmask_b32_e32 v13, v13, v85, vcc
	v_cndmask_b32_e32 v14, v14, v86, vcc
	v_cndmask_b32_e32 v15, v15, v87, vcc
	v_cndmask_b32_e32 v16, v16, v88, vcc
	v_cndmask_b32_e32 v17, v17, v89, vcc
	v_readlane_b32 s18, v80, 7
	s_cmp_ge_u32 s14, 7
	s_cselect_b64 vcc, -1, 0
	s_waitcnt vmcnt(0)
	v_lshlrev_b32_e32 v82, 16, v76
	v_and_b32_e32 v83, 0xffff0000, v76
	v_lshlrev_b32_e32 v84, 16, v77
	v_and_b32_e32 v85, 0xffff0000, v77
	v_lshlrev_b32_e32 v86, 16, v78
	v_and_b32_e32 v87, 0xffff0000, v78
	v_lshlrev_b32_e32 v88, 16, v79
	v_and_b32_e32 v89, 0xffff0000, v79
	v_cndmask_b32_e32 v81, 0, v47, vcc
	v_pk_mul_f32 v[82:83], v[6:7], v[82:83]
	v_pk_mul_f32 v[84:85], v[8:9], v[84:85]
	v_pk_mul_f32 v[86:87], v[2:3], v[86:87]
	v_pk_mul_f32 v[88:89], v[4:5], v[88:89]
	s_cmp_eq_u32 s14, 7
	s_cselect_b64 vcc, -1, 0
	v_mul_f32_e32 v82, s18, v82
	v_mul_f32_e32 v83, s18, v83
	v_mul_f32_e32 v84, s18, v84
	v_mul_f32_e32 v85, s18, v85
	v_mul_f32_e32 v86, s18, v86
	v_mul_f32_e32 v87, s18, v87
	v_mul_f32_e32 v88, s18, v88
	v_mul_f32_e32 v89, s18, v89
	v_fmac_f32_e32 v22, v81, v82
	v_fmac_f32_e32 v23, v81, v83
	v_fmac_f32_e32 v26, v81, v84
	v_fmac_f32_e32 v27, v81, v85
	v_fmac_f32_e32 v20, v81, v86
	v_fmac_f32_e32 v21, v81, v87
	v_fmac_f32_e32 v24, v81, v88
	v_fmac_f32_e32 v25, v81, v89
	v_cndmask_b32_e32 v10, v10, v82, vcc
	v_cndmask_b32_e32 v11, v11, v83, vcc
	v_cndmask_b32_e32 v12, v12, v84, vcc
	v_cndmask_b32_e32 v13, v13, v85, vcc
	v_cndmask_b32_e32 v14, v14, v86, vcc
	v_cndmask_b32_e32 v15, v15, v87, vcc
	v_cndmask_b32_e32 v16, v16, v88, vcc
	v_cndmask_b32_e32 v17, v17, v89, vcc
	s_branch .LBB0_607
